# scan: younger producer wave of each SIMD at priority 2 (immediate-only change)
# baseline (speedup 1.0000x reference)
; __device__ __forceinline__ void lds_barrier() { asm volatile("s_waitcnt lgkmcnt(0)" ::: "memory"); __builtin_amdgcn_s_barrier(); asm volatile("" ::: "memory"); }
; __device__ __forceinline__ void phase_scan2(const Params& p, int l, LAS unsigned char* lds) {
;     ...
;         if (wid >= 3) { pload(pw); pbuild(pw, lds + pw * SC_SLOT, scr, SC_NP + pw); }
;         lds_barrier();
;         for (int rd = 0; rd < NRD; ++rd) {
;             if (wid == 0) {
; #pragma unroll 1
;                 for (int q = 0; q < SC_NP; ++q) { const int c = rd * SC_NP + q; if (c < NCH) consume(c, lds + ((rd & 1) * SC_NP + q) * SC_SLOT); }
;             } else if (wid >= 3) {
;                 const int cb = (rd + 1) * SC_NP + pw, cn = cb + SC_NP;
;                 if (cb < NCH) pbuild(cb, lds + (((rd + 1) & 1) * SC_NP + pw) * SC_SLOT, scr, cn < NCH ? cn : -1);
.Lsc_producer:
	s_sub_u32 s55, s25, 1
	s_cmp_gt_u32 s25, 4
	s_cselect_b32 s0, 1, 0
	s_sub_u32 s55, s55, s0
	s_cmp_gt_u32 s25, 4
	s_cbranch_scc0 .Lsc_p_noprio
	s_setprio 2
